# FoX main loop: next K/V tile global loads issued at the top of each half-step (before K Q^T) instead of after finishSM; compiler temp v160->v208; conservative vmcnt guards shifted by 4
# baseline (speedup 1.0000x reference)
;     ...
;     const char* kb[4];
; #pragma unroll
;     for (int dd = 0; dd < 4; ++dd) kb[dd] = K_lds + KB * SHM_K + KSWZ(r32, (dd * 16 + hi * 8) * 2);
; #pragma unroll
;     for (int d0 = 0; d0 < 8; ++d0) { const char* a = kb[d0 & 3] + (d0 >> 2) * 128;
;         bf16x8 b0 = *reinterpret_cast<const bf16x8*>(a);
;         bf16x8 b1 = *reinterpret_cast<const bf16x8*>(a + 32 * 256);
;         bf16x8 q; if (d0 < 8 - QL) q = qr[d0]; else q = *reinterpret_cast<const bf16x8*>(qlds + (d0 - (8 - QL)) * 1024);
;         p0 = __builtin_amdgcn_mfma_f32_32x32x16_bf16(b0, q, p0, 0, 0, 0);
;         p1 = __builtin_amdgcn_mfma_f32_32x32x16_bf16(b1, q, p1, 0, 0, 0); }
.LBB0_1176:
	s_add_i32 s35, s84, 1
	s_mul_hi_i32 s39, s35, 0x6000
	s_mulk_i32 s35, 0x6000
	s_add_u32 vcc_lo, s20, s35
	s_addc_u32 vcc_hi, s21, s39
	s_add_u32 s38, s22, s35
	s_addc_u32 s39, s23, s39
	v_lshl_add_u64 v[160:161], s[38:39], 0, v[176:177]
	v_lshl_add_u64 v[164:165], s[38:39], 0, v[178:179]
	v_lshl_add_u64 v[168:169], vcc, 0, v[176:177]
	v_lshl_add_u64 v[172:173], vcc, 0, v[178:179]
	global_load_dwordx4 v[160:163], v[160:161], off
	s_nop 0
	global_load_dwordx4 v[164:167], v[164:165], off
	s_nop 0
	global_load_dwordx4 v[168:171], v[168:169], off
	s_nop 0
	global_load_dwordx4 v[172:175], v[172:173], off
	s_add_i32 s73, s72, 1
	s_cmp_ge_i32 s73, s30
	s_cselect_b64 s[10:11], -1, 0
	s_cmp_le_i32 s73, s31
	s_cselect_b64 s[12:13], -1, 0
	s_and_b64 s[12:13], s[10:11], s[12:13]
	s_waitcnt vmcnt(7)
	v_cndmask_b32_e64 v208, 0, 1, s[12:13]
	v_cmp_ne_u32_e64 s[10:11], 1, v208
	s_andn2_b64 vcc, exec, s[12:13]
	s_cbranch_vccnz .LBB0_1178
	ds_read_b128 v[80:83], v202
	ds_read_b128 v[84:87], v202 offset:32
	ds_read_b128 v[88:91], v202 offset:64
	ds_read_b128 v[92:95], v202 offset:96
	ds_read_b128 v[64:67], v202 offset:128
	ds_read_b128 v[68:71], v202 offset:160
	ds_read_b128 v[72:75], v202 offset:192
	ds_read_b128 v[76:79], v202 offset:224
	ds_read_b128 v[224:227], v204 offset:49152
	ds_read_b128 v[228:231], v204 offset:57344
	ds_read_b128 v[232:235], v205 offset:49152
	ds_read_b128 v[236:239], v205 offset:57344
	s_waitcnt lgkmcnt(3)
	v_mfma_f32_32x32x16_bf16 v[80:95], v[224:227], v[140:143], v[80:95]
	ds_read_b128 v[224:227], v206 offset:49152
	s_waitcnt lgkmcnt(3)
	v_mfma_f32_32x32x16_bf16 v[64:79], v[228:231], v[140:143], v[64:79]
	ds_read_b128 v[228:231], v206 offset:57344
	s_waitcnt lgkmcnt(3)
	v_mfma_f32_32x32x16_bf16 v[80:95], v[232:235], v[132:135], v[80:95]
	ds_read_b128 v[232:235], v207 offset:49152
	s_waitcnt lgkmcnt(3)
	v_mfma_f32_32x32x16_bf16 v[64:79], v[236:239], v[132:135], v[64:79]
	ds_read_b128 v[236:239], v207 offset:57344
	s_waitcnt lgkmcnt(3)
	v_mfma_f32_32x32x16_bf16 v[80:95], v[224:227], v[136:139], v[80:95]
	ds_read_b128 v[240:243], v195
	ds_read_b128 v[224:227], v204 offset:49280
	s_waitcnt lgkmcnt(4)
	v_mfma_f32_32x32x16_bf16 v[64:79], v[228:231], v[136:139], v[64:79]
	ds_read_b128 v[228:231], v204 offset:57472
	s_waitcnt lgkmcnt(4)
	v_mfma_f32_32x32x16_bf16 v[80:95], v[232:235], v[128:131], v[80:95]
	ds_read_b128 v[244:247], v195 offset:1024
	ds_read_b128 v[232:235], v205 offset:49280
	s_waitcnt lgkmcnt(5)
	v_mfma_f32_32x32x16_bf16 v[64:79], v[236:239], v[128:131], v[64:79]
	ds_read_b128 v[236:239], v205 offset:57472
	s_waitcnt vmcnt(6)
	s_waitcnt lgkmcnt(4)
	v_mfma_f32_32x32x16_bf16 v[80:95], v[224:227], v[240:243], v[80:95]
	ds_read_b128 v[224:227], v206 offset:49280
	s_waitcnt lgkmcnt(4)
	v_mfma_f32_32x32x16_bf16 v[64:79], v[228:231], v[240:243], v[64:79]
	ds_read_b128 v[240:243], v195 offset:2048
	ds_read_b128 v[228:231], v206 offset:57472
	s_waitcnt lgkmcnt(4)
	v_mfma_f32_32x32x16_bf16 v[80:95], v[232:235], v[244:247], v[80:95]
	ds_read_b128 v[232:235], v207 offset:49280
	s_waitcnt lgkmcnt(4)
	v_mfma_f32_32x32x16_bf16 v[64:79], v[236:239], v[244:247], v[64:79]
	ds_read_b128 v[244:247], v195 offset:3072
	ds_read_b128 v[236:239], v207 offset:57472
	s_waitcnt lgkmcnt(4)
	v_mfma_f32_32x32x16_bf16 v[80:95], v[224:227], v[240:243], v[80:95]
	s_waitcnt lgkmcnt(3)
	v_mfma_f32_32x32x16_bf16 v[64:79], v[228:231], v[240:243], v[64:79]
	s_waitcnt lgkmcnt(1)
	v_mfma_f32_32x32x16_bf16 v[80:95], v[232:235], v[244:247], v[80:95]
	s_waitcnt lgkmcnt(0)
	v_mfma_f32_32x32x16_bf16 v[64:79], v[236:239], v[244:247], v[64:79]
; __device__ __forceinline__ void finishSM(f32x16& p0, f32x16& p1, float alpha, float& l_reg, bf16x8& pa0, bf16x8& pa1, bf16x8& pa2, bf16x8& pa3) {
; #pragma unroll
;     for (int r = 0; r < 16; ++r) p1[r] = __builtin_amdgcn_exp2f(p1[r]);
;     float ps = 0;
; #pragma unroll
;     for (int r = 0; r < 16; ++r) ps += p0[r];
; #pragma unroll
;     for (int r = 0; r < 16; ++r) ps += p1[r];
;     { auto rr = __builtin_amdgcn_permlane32_swap(__float_as_uint(ps), __float_as_uint(ps), false, false);
;       ps = __uint_as_float(rr[0]) + __uint_as_float(rr[1]); }
;     l_reg = l_reg * alpha + ps;
;     PK4(p0, 0, pa0); PK4(p0, 8, pa1); PK4(p1, 0, pa2); PK4(p1, 8, pa3);
; }
; template <int VB>
; __device__ __forceinline__ void pv_tile(f32x16* o, int vb0, bf16x8 pa0, bf16x8 pa1, bf16x8 pa2, bf16x8 pa3) {
;     ...
;     PV_D0(0); PV_D0(1); PV_D0(2); PV_D0(3);
.LBB0_1178:
	s_cmp_gt_i32 s73, s30
	s_cselect_b64 s[12:13], -1, 0
	s_cmp_le_i32 s72, s31
	s_cselect_b64 vcc, -1, 0
	s_and_b64 vcc, s[12:13], vcc
	v_cndmask_b32_e64 v208, 0, 1, vcc
	v_cmp_ne_u32_e64 s[12:13], 1, v208
	s_andn2_b64 vcc, exec, vcc
	s_cbranch_vccnz .LBB0_1180
	s_waitcnt vmcnt(7)
	v_add_f32_e32 v144, 0, v112
	v_add_f32_e32 v144, v113, v144
	v_add_f32_e32 v144, v114, v144
	v_add_f32_e32 v144, v115, v144
	v_add_f32_e32 v144, v116, v144
	v_add_f32_e32 v144, v117, v144
	v_add_f32_e32 v144, v118, v144
	v_add_f32_e32 v144, v119, v144
	v_add_f32_e32 v144, v120, v144
	v_add_f32_e32 v144, v121, v144
	v_add_f32_e32 v144, v122, v144
	v_add_f32_e32 v144, v123, v144
	v_exp_f32_e32 v96, v96
	v_add_f32_e32 v144, v124, v144
	v_exp_f32_e32 v97, v97
	v_add_f32_e32 v144, v125, v144
	v_exp_f32_e32 v98, v98
	v_add_f32_e32 v144, v126, v144
	v_exp_f32_e32 v99, v99
	v_add_f32_e32 v144, v127, v144
	v_exp_f32_e32 v100, v100
	v_add_f32_e32 v144, v96, v144
	v_exp_f32_e32 v101, v101
	v_add_f32_e32 v144, v97, v144
	v_exp_f32_e32 v102, v102
	v_add_f32_e32 v144, v98, v144
	v_exp_f32_e32 v103, v103
	v_add_f32_e32 v144, v99, v144
	v_exp_f32_e32 v104, v104
	v_add_f32_e32 v144, v100, v144
	v_exp_f32_e32 v105, v105
	v_add_f32_e32 v144, v101, v144
	v_exp_f32_e32 v106, v106
	v_add_f32_e32 v144, v102, v144
	v_exp_f32_e32 v107, v107
	v_add_f32_e32 v144, v103, v144
	v_exp_f32_e32 v108, v108
	v_add_f32_e32 v144, v104, v144
	v_exp_f32_e32 v109, v109
	v_add_f32_e32 v144, v105, v144
	v_exp_f32_e32 v110, v110
	v_add_f32_e32 v144, v106, v144
	v_exp_f32_e32 v111, v111
	v_add_f32_e32 v144, v107, v144
	v_add_f32_e32 v144, v108, v144
	v_add_f32_e32 v144, v109, v144
	v_add_f32_e32 v144, v110, v144
	v_add_f32_e32 v144, v111, v144
	v_mov_b32_e32 v145, v144
	s_nop 1
	v_permlane32_swap_b32_e32 v144, v145
	v_add_f32_e32 v208, v144, v145
	v_fmac_f32_e32 v208, v201, v196
	v_cvt_pk_bf16_f32 v144, v112, v113
	v_cvt_pk_bf16_f32 v145, v114, v115
	v_cvt_pk_bf16_f32 v146, v116, v117
	v_cvt_pk_bf16_f32 v147, v118, v119
	s_waitcnt vmcnt(5)
	v_cvt_pk_bf16_f32 v148, v120, v121
	v_cvt_pk_bf16_f32 v149, v122, v123
	v_cvt_pk_bf16_f32 v150, v124, v125
	v_cvt_pk_bf16_f32 v151, v126, v127
	v_cvt_pk_bf16_f32 v152, v96, v97
	v_cvt_pk_bf16_f32 v153, v98, v99
	v_cvt_pk_bf16_f32 v154, v100, v101
	v_cvt_pk_bf16_f32 v155, v102, v103
	s_waitcnt vmcnt(4)
	v_cvt_pk_bf16_f32 v156, v104, v105
	v_cvt_pk_bf16_f32 v157, v106, v107
	v_cvt_pk_bf16_f32 v158, v108, v109
	v_cvt_pk_bf16_f32 v159, v110, v111
	v_permlane32_swap_b32_e32 v144, v146
	v_permlane32_swap_b32_e32 v145, v147
	v_permlane32_swap_b32_e32 v148, v150
	v_permlane32_swap_b32_e32 v149, v151
	v_permlane32_swap_b32_e32 v152, v154
	v_permlane32_swap_b32_e32 v153, v155
	v_permlane32_swap_b32_e32 v156, v158
	v_permlane32_swap_b32_e32 v157, v159
	v_mov_b32_e32 v196, v208
.LBB0_1180:
	s_and_b64 vcc, exec, s[12:13]
	s_cbranch_vccnz .LBB0_1182
	ds_read_b64_tr_b16 v[208:209], v192 offset:0
	ds_read_b64_tr_b16 v[210:211], v192 offset:0x800
	ds_read_b64_tr_b16 v[212:213], v192 offset:0x1000
	ds_read_b64_tr_b16 v[214:215], v192 offset:0x1800
	ds_read_b64_tr_b16 v[216:217], v192 offset:0x2000
	ds_read_b64_tr_b16 v[218:219], v192 offset:0x2800
	ds_read_b64_tr_b16 v[220:221], v192 offset:0x3000
	ds_read_b64_tr_b16 v[222:223], v192 offset:0x3800
	s_waitcnt lgkmcnt(6)
	s_waitcnt vmcnt(7)
	v_mfma_f32_32x32x16_bf16 v[32:47], v[144:147], v[208:211], v[32:47]
	ds_read_b64_tr_b16 v[208:209], v192 offset:0x200
	ds_read_b64_tr_b16 v[210:211], v192 offset:0xa00
	s_waitcnt vmcnt(5)
	s_waitcnt lgkmcnt(6)
	v_mfma_f32_32x32x16_bf16 v[32:47], v[148:151], v[212:215], v[32:47]
	ds_read_b64_tr_b16 v[212:213], v192 offset:0x1200
	ds_read_b64_tr_b16 v[214:215], v192 offset:0x1a00
	s_waitcnt lgkmcnt(6)
	v_mfma_f32_32x32x16_bf16 v[32:47], v[152:155], v[216:219], v[32:47]
	ds_read_b64_tr_b16 v[216:217], v192 offset:0x2200
	ds_read_b64_tr_b16 v[218:219], v192 offset:0x2a00
	s_waitcnt vmcnt(4)
	s_waitcnt lgkmcnt(6)
	v_mfma_f32_32x32x16_bf16 v[32:47], v[156:159], v[220:223], v[32:47]
	ds_read_b64_tr_b16 v[220:221], v192 offset:0x3200
	ds_read_b64_tr_b16 v[222:223], v192 offset:0x3a00
	s_waitcnt lgkmcnt(6)
	v_mfma_f32_32x32x16_bf16 v[48:63], v[144:147], v[208:211], v[48:63]
	ds_read_b64_tr_b16 v[208:209], v192 offset:0x400
	ds_read_b64_tr_b16 v[210:211], v192 offset:0xc00
	s_waitcnt lgkmcnt(6)
	v_mfma_f32_32x32x16_bf16 v[48:63], v[148:151], v[212:215], v[48:63]
	ds_read_b64_tr_b16 v[212:213], v192 offset:0x1400
	ds_read_b64_tr_b16 v[214:215], v192 offset:0x1c00
	s_waitcnt lgkmcnt(6)
	v_mfma_f32_32x32x16_bf16 v[48:63], v[152:155], v[216:219], v[48:63]
	ds_read_b64_tr_b16 v[216:217], v192 offset:0x2400
	ds_read_b64_tr_b16 v[218:219], v192 offset:0x2c00
	s_waitcnt lgkmcnt(6)
	v_mfma_f32_32x32x16_bf16 v[48:63], v[156:159], v[220:223], v[48:63]
	ds_read_b64_tr_b16 v[220:221], v192 offset:0x3400
	ds_read_b64_tr_b16 v[222:223], v192 offset:0x3c00
	s_waitcnt lgkmcnt(6)
	v_mfma_f32_32x32x16_bf16 v[16:31], v[144:147], v[208:211], v[16:31]
	ds_read_b64_tr_b16 v[208:209], v192 offset:0x600
	ds_read_b64_tr_b16 v[210:211], v192 offset:0xe00
	s_waitcnt lgkmcnt(6)
	v_mfma_f32_32x32x16_bf16 v[16:31], v[148:151], v[212:215], v[16:31]
	ds_read_b64_tr_b16 v[212:213], v192 offset:0x1600
	ds_read_b64_tr_b16 v[214:215], v192 offset:0x1e00
	s_waitcnt lgkmcnt(6)
	v_mfma_f32_32x32x16_bf16 v[16:31], v[152:155], v[216:219], v[16:31]
	ds_read_b64_tr_b16 v[216:217], v192 offset:0x2600
	ds_read_b64_tr_b16 v[218:219], v192 offset:0x2e00
	s_waitcnt lgkmcnt(6)
	v_mfma_f32_32x32x16_bf16 v[16:31], v[156:159], v[220:223], v[16:31]
	ds_read_b64_tr_b16 v[220:221], v192 offset:0x3600
	ds_read_b64_tr_b16 v[222:223], v192 offset:0x3e00
	s_waitcnt lgkmcnt(6)
	v_mfma_f32_32x32x16_bf16 v[0:15], v[144:147], v[208:211], v[0:15]
	s_waitcnt lgkmcnt(4)
	v_mfma_f32_32x32x16_bf16 v[0:15], v[148:151], v[212:215], v[0:15]
	s_waitcnt lgkmcnt(2)
	v_mfma_f32_32x32x16_bf16 v[0:15], v[152:155], v[216:219], v[0:15]
	s_waitcnt lgkmcnt(0)
	v_mfma_f32_32x32x16_bf16 v[0:15], v[156:159], v[220:223], v[0:15]

;     ...
;     const char* kb[4];
; #pragma unroll
;     for (int dd = 0; dd < 4; ++dd) kb[dd] = K_lds + KB * SHM_K + KSWZ(r32, (dd * 16 + hi * 8) * 2);
; #pragma unroll
;     for (int d0 = 0; d0 < 8; ++d0) { const char* a = kb[d0 & 3] + (d0 >> 2) * 128;
;         bf16x8 b0 = *reinterpret_cast<const bf16x8*>(a);
;         bf16x8 b1 = *reinterpret_cast<const bf16x8*>(a + 32 * 256);
;         bf16x8 q; if (d0 < 8 - QL) q = qr[d0]; else q = *reinterpret_cast<const bf16x8*>(qlds + (d0 - (8 - QL)) * 1024);
;         p0 = __builtin_amdgcn_mfma_f32_32x32x16_bf16(b0, q, p0, 0, 0, 0);
;         p1 = __builtin_amdgcn_mfma_f32_32x32x16_bf16(b1, q, p1, 0, 0, 0); }
.LBB0_1191:
	s_add_i32 s35, s72, 2
	s_waitcnt lgkmcnt(0)
	s_barrier
	s_add_i32 s38, s72, 3
	s_cmp_ge_i32 s38, s55
	s_cbranch_scc1 .Lfox_nold_b
	s_add_i32 s38, s84, 0x41
	s_mul_i32 vcc_lo, s38, 0x6000
	s_mul_hi_i32 vcc_hi, s38, 0x6000
	s_add_u32 s38, s20, vcc_lo
	s_addc_u32 s39, s21, vcc_hi
	s_add_u32 vcc_lo, s22, vcc_lo
	s_addc_u32 vcc_hi, s23, vcc_hi
	v_lshl_add_u64 v[160:161], vcc, 0, v[176:177]
	v_lshl_add_u64 v[164:165], vcc, 0, v[178:179]
	v_lshl_add_u64 v[168:169], s[38:39], 0, v[176:177]
	v_lshl_add_u64 v[172:173], s[38:39], 0, v[178:179]
	global_load_dwordx4 v[160:163], v[160:161], off
	s_nop 0
	global_load_dwordx4 v[164:167], v[164:165], off
	s_nop 0
	global_load_dwordx4 v[168:171], v[168:169], off
	s_nop 0
	global_load_dwordx4 v[172:175], v[172:173], off
.Lfox_nold_b:
	s_cmp_ge_i32 s35, s30
	s_cselect_b64 s[12:13], -1, 0
	s_cmp_lt_i32 s73, s31
	s_cselect_b64 s[38:39], -1, 0
	s_and_b64 s[38:39], s[12:13], s[38:39]
	v_cndmask_b32_e64 v208, 0, 1, s[38:39]
	v_cmp_ne_u32_e64 s[12:13], 1, v208
	s_andn2_b64 vcc, exec, s[38:39]
	s_cbranch_vccnz .LBB0_1193
	ds_read_b128 v[112:115], v202 offset:256
	ds_read_b128 v[116:119], v202 offset:288
	ds_read_b128 v[120:123], v202 offset:320
	ds_read_b128 v[124:127], v202 offset:352
	ds_read_b128 v[96:99], v202 offset:384
	ds_read_b128 v[100:103], v202 offset:416
	ds_read_b128 v[104:107], v202 offset:448
	ds_read_b128 v[108:111], v202 offset:480
	ds_read_b128 v[224:227], v204 offset:32768
	ds_read_b128 v[228:231], v204 offset:40960
	ds_read_b128 v[232:235], v205 offset:32768
	ds_read_b128 v[236:239], v205 offset:40960
	s_waitcnt lgkmcnt(3)
	v_mfma_f32_32x32x16_bf16 v[112:127], v[224:227], v[140:143], v[112:127]
	ds_read_b128 v[224:227], v206 offset:32768
	s_waitcnt lgkmcnt(3)
	v_mfma_f32_32x32x16_bf16 v[96:111], v[228:231], v[140:143], v[96:111]
	ds_read_b128 v[228:231], v206 offset:40960
	s_waitcnt lgkmcnt(3)
	v_mfma_f32_32x32x16_bf16 v[112:127], v[232:235], v[132:135], v[112:127]
	ds_read_b128 v[232:235], v207 offset:32768
	s_waitcnt lgkmcnt(3)
	v_mfma_f32_32x32x16_bf16 v[96:111], v[236:239], v[132:135], v[96:111]
	ds_read_b128 v[236:239], v207 offset:40960
	s_waitcnt lgkmcnt(3)
	v_mfma_f32_32x32x16_bf16 v[112:127], v[224:227], v[136:139], v[112:127]
	ds_read_b128 v[240:243], v195
	ds_read_b128 v[224:227], v204 offset:32896
	s_waitcnt lgkmcnt(4)
	v_mfma_f32_32x32x16_bf16 v[96:111], v[228:231], v[136:139], v[96:111]
	ds_read_b128 v[228:231], v204 offset:41088
	s_waitcnt lgkmcnt(4)
	v_mfma_f32_32x32x16_bf16 v[112:127], v[232:235], v[128:131], v[112:127]
	ds_read_b128 v[244:247], v195 offset:1024
	ds_read_b128 v[232:235], v205 offset:32896
	s_waitcnt lgkmcnt(5)
	v_mfma_f32_32x32x16_bf16 v[96:111], v[236:239], v[128:131], v[96:111]
	ds_read_b128 v[236:239], v205 offset:41088
	s_waitcnt lgkmcnt(4)
	v_mfma_f32_32x32x16_bf16 v[112:127], v[224:227], v[240:243], v[112:127]
	ds_read_b128 v[224:227], v206 offset:32896
	s_waitcnt lgkmcnt(4)
	v_mfma_f32_32x32x16_bf16 v[96:111], v[228:231], v[240:243], v[96:111]
	ds_read_b128 v[240:243], v195 offset:2048
	ds_read_b128 v[228:231], v206 offset:41088
	s_waitcnt lgkmcnt(4)
	v_mfma_f32_32x32x16_bf16 v[112:127], v[232:235], v[244:247], v[112:127]
	ds_read_b128 v[232:235], v207 offset:32896
	s_waitcnt lgkmcnt(4)
	v_mfma_f32_32x32x16_bf16 v[96:111], v[236:239], v[244:247], v[96:111]
	ds_read_b128 v[244:247], v195 offset:3072
	ds_read_b128 v[236:239], v207 offset:41088
	s_waitcnt lgkmcnt(4)
	v_mfma_f32_32x32x16_bf16 v[112:127], v[224:227], v[240:243], v[112:127]
	s_waitcnt lgkmcnt(3)
	v_mfma_f32_32x32x16_bf16 v[96:111], v[228:231], v[240:243], v[96:111]
	s_waitcnt lgkmcnt(1)
	v_mfma_f32_32x32x16_bf16 v[112:127], v[232:235], v[244:247], v[112:127]
	s_waitcnt lgkmcnt(0)
	v_mfma_f32_32x32x16_bf16 v[96:111], v[236:239], v[244:247], v[96:111]

; template <int VB>
; __device__ __forceinline__ void pv_tile(f32x16* o, int vb0, bf16x8 pa0, bf16x8 pa1, bf16x8 pa2, bf16x8 pa3) {
;     ...
;     PV_D0(0); PV_D0(1); PV_D0(2); PV_D0(3);
.LBB0_1197:
	s_and_b64 vcc, exec, s[12:13]
	s_cbranch_vccz .LBB0_1200
	s_branch .LBB0_1203
.LBB0_1198:
	s_and_b64 vcc, exec, s[10:11]
	s_cbranch_vccnz .LBB0_1197
.LBB0_1199:
	ds_read_b64_tr_b16 v[208:209], v192 offset:0x4000
	ds_read_b64_tr_b16 v[210:211], v192 offset:0x4800
	ds_read_b64_tr_b16 v[212:213], v192 offset:0x5000
	ds_read_b64_tr_b16 v[214:215], v192 offset:0x5800
	ds_read_b64_tr_b16 v[216:217], v192 offset:0x6000
	ds_read_b64_tr_b16 v[218:219], v192 offset:0x6800
	ds_read_b64_tr_b16 v[220:221], v192 offset:0x7000
	ds_read_b64_tr_b16 v[222:223], v192 offset:0x7800
	s_waitcnt lgkmcnt(6)
	s_nop 0
	v_mfma_f32_32x32x16_bf16 v[32:47], v[144:147], v[208:211], v[32:47]
	ds_read_b64_tr_b16 v[208:209], v192 offset:0x4200
	ds_read_b64_tr_b16 v[210:211], v192 offset:0x4a00
	s_waitcnt lgkmcnt(6)
	v_mfma_f32_32x32x16_bf16 v[32:47], v[148:151], v[212:215], v[32:47]
	ds_read_b64_tr_b16 v[212:213], v192 offset:0x5200
	ds_read_b64_tr_b16 v[214:215], v192 offset:0x5a00
	s_waitcnt lgkmcnt(6)
	v_mfma_f32_32x32x16_bf16 v[32:47], v[152:155], v[216:219], v[32:47]
	ds_read_b64_tr_b16 v[216:217], v192 offset:0x6200
	ds_read_b64_tr_b16 v[218:219], v192 offset:0x6a00
	s_waitcnt lgkmcnt(6)
	v_mfma_f32_32x32x16_bf16 v[32:47], v[156:159], v[220:223], v[32:47]
	ds_read_b64_tr_b16 v[220:221], v192 offset:0x7200
	ds_read_b64_tr_b16 v[222:223], v192 offset:0x7a00
	s_waitcnt lgkmcnt(6)
	v_mfma_f32_32x32x16_bf16 v[48:63], v[144:147], v[208:211], v[48:63]
	ds_read_b64_tr_b16 v[208:209], v192 offset:0x4400
	ds_read_b64_tr_b16 v[210:211], v192 offset:0x4c00
	s_waitcnt lgkmcnt(6)
	v_mfma_f32_32x32x16_bf16 v[48:63], v[148:151], v[212:215], v[48:63]
	ds_read_b64_tr_b16 v[212:213], v192 offset:0x5400
	ds_read_b64_tr_b16 v[214:215], v192 offset:0x5c00
	s_waitcnt lgkmcnt(6)
	v_mfma_f32_32x32x16_bf16 v[48:63], v[152:155], v[216:219], v[48:63]
	ds_read_b64_tr_b16 v[216:217], v192 offset:0x6400
	ds_read_b64_tr_b16 v[218:219], v192 offset:0x6c00
	s_waitcnt lgkmcnt(6)
	v_mfma_f32_32x32x16_bf16 v[48:63], v[156:159], v[220:223], v[48:63]
	ds_read_b64_tr_b16 v[220:221], v192 offset:0x7400
	ds_read_b64_tr_b16 v[222:223], v192 offset:0x7c00
	s_waitcnt lgkmcnt(6)
	v_mfma_f32_32x32x16_bf16 v[16:31], v[144:147], v[208:211], v[16:31]
	ds_read_b64_tr_b16 v[208:209], v192 offset:0x4600
	ds_read_b64_tr_b16 v[210:211], v192 offset:0x4e00
	s_waitcnt lgkmcnt(6)
	v_mfma_f32_32x32x16_bf16 v[16:31], v[148:151], v[212:215], v[16:31]
	ds_read_b64_tr_b16 v[212:213], v192 offset:0x5600
	ds_read_b64_tr_b16 v[214:215], v192 offset:0x5e00
	s_waitcnt lgkmcnt(6)
	v_mfma_f32_32x32x16_bf16 v[16:31], v[152:155], v[216:219], v[16:31]
	ds_read_b64_tr_b16 v[216:217], v192 offset:0x6600
	ds_read_b64_tr_b16 v[218:219], v192 offset:0x6e00
	s_waitcnt lgkmcnt(6)
	v_mfma_f32_32x32x16_bf16 v[16:31], v[156:159], v[220:223], v[16:31]
	ds_read_b64_tr_b16 v[220:221], v192 offset:0x7600
	ds_read_b64_tr_b16 v[222:223], v192 offset:0x7e00
	s_waitcnt lgkmcnt(6)
	v_mfma_f32_32x32x16_bf16 v[0:15], v[144:147], v[208:211], v[0:15]
	s_waitcnt lgkmcnt(4)
	v_mfma_f32_32x32x16_bf16 v[0:15], v[148:151], v[212:215], v[0:15]
	s_waitcnt lgkmcnt(2)
	v_mfma_f32_32x32x16_bf16 v[0:15], v[152:155], v[216:219], v[0:15]
	s_waitcnt lgkmcnt(0)
	v_mfma_f32_32x32x16_bf16 v[0:15], v[156:159], v[220:223], v[0:15]
	s_and_b64 vcc, exec, s[12:13]
	s_cbranch_vccnz .LBB0_1203
